# attnA loop: raised wave priority over the S-MFMA and PV-MFMA regions, normal priority over the exp stretch
# speedup vs baseline: 1.0076x; 1.0024x over previous
; __device__ __forceinline__ unsigned cvtpk(float lo, float hi) { f32x2_t v = {lo, hi}; bf16x2_t b = __builtin_convertvector(v, bf16x2_t); return __builtin_bit_cast(unsigned, b); }
; template <int DH, int KT, int NQT, bool PF, class Ctx>
; __device__ __forceinline__ void attn_item(unsigned char* smem, const Ctx& c) {
;     ...
;           float psum = 0.f;
; #pragma unroll
;           for (int k4 = 0; k4 < NK4; ++k4)
; #pragma unroll
;             for (int j = 0; j < 4; ++j) { const float pv = __builtin_amdgcn_exp2f(s[q][k4][j] - mnew); s[q][k4][j] = pv; psum += pv; }
;           lrow[qt] += psum;
; #pragma unroll
;           for (int kk = 0; kk < NKK; ++kk) {
;             u32x4 w;
;             w.x = cvtpk(s[q][2 * kk][0], s[q][2 * kk][1]); w.y = cvtpk(s[q][2 * kk][2], s[q][2 * kk][3]);
;             w.z = cvtpk(s[q][2 * kk + 1][0], s[q][2 * kk + 1][1]); w.w = cvtpk(s[q][2 * kk + 1][2], s[q][2 * kk + 1][3]);
;             pfa[qt][kk] = __builtin_bit_cast(bf16x8, w);
;           }
;         }
;       }
; #pragma unroll
;       for (int kk = 0; kk < NKK; ++kk) {
;         const bf16_t* vb = sV + (32 * kk + 4 * quad + (l15 >> 2)) * LDK + 4 * (l15 & 3);
; #pragma unroll
;         for (int dt = 0; dt < NDT; ++dt) {
;           const s16x4 lo = tr_read(vb + 16 * dt);
;           const s16x4 hi = tr_read(vb + 16 * LDK + 16 * dt);
;           const bf16x8 vf = (bf16x8){lo[0], lo[1], lo[2], lo[3], hi[0], hi[1], hi[2], hi[3]};
.LBB0_212:
	s_setprio 0
	v_mov_b32_e32 v249, 0
	v_exp_f32_e32 v169, v184
	v_exp_f32_e32 v170, v185
	v_exp_f32_e32 v171, v186
	v_exp_f32_e32 v173, v187
	v_add_f32_e32 v174, 0, v169
	v_exp_f32_e32 v175, v176
	v_add_f32_e32 v174, v170, v174
	v_exp_f32_e32 v176, v177
	v_add_f32_e32 v174, v171, v174
	v_exp_f32_e32 v177, v178
	v_add_f32_e32 v174, v173, v174
	v_exp_f32_e32 v178, v179
	v_add_f32_e32 v174, v175, v174
	v_exp_f32_e32 v179, v164
	v_add_f32_e32 v174, v176, v174
	v_exp_f32_e32 v180, v165
	v_add_f32_e32 v174, v177, v174
	v_exp_f32_e32 v181, v166
	v_add_f32_e32 v174, v178, v174
	v_exp_f32_e32 v182, v167
	v_add_f32_e32 v164, v179, v174
	v_exp_f32_e32 v174, v156
	v_exp_f32_e32 v144, v144
	v_add_f32_e32 v164, v180, v164
	v_exp_f32_e32 v145, v145
	v_add_f32_e32 v164, v181, v164
	v_exp_f32_e32 v183, v157
	v_exp_f32_e32 v146, v146
	v_add_f32_e32 v164, v182, v164
	v_exp_f32_e32 v184, v158
	v_exp_f32_e32 v147, v147
	v_exp_f32_e32 v159, v159
	v_add_f32_e32 v156, v174, v164
	v_cvt_pk_bf16_f32 v164, v169, v170
	v_add_f32_e32 v169, 0, v144
	v_exp_f32_e32 v140, v140
	v_add_f32_e32 v169, v145, v169
	v_exp_f32_e32 v141, v141
	v_add_f32_e32 v169, v146, v169
	v_exp_f32_e32 v142, v142
	v_add_f32_e32 v169, v147, v169
	v_exp_f32_e32 v143, v143
	v_add_f32_e32 v169, v140, v169
	v_exp_f32_e32 v152, v152
	v_add_f32_e32 v169, v141, v169
	v_exp_f32_e32 v153, v153
	v_add_f32_e32 v169, v142, v169
	v_exp_f32_e32 v154, v154
	v_add_f32_e32 v169, v143, v169
	v_exp_f32_e32 v155, v155
	v_add_f32_e32 v169, v152, v169
	v_exp_f32_e32 v170, v148
	v_add_f32_e32 v169, v153, v169
	v_cvt_pk_bf16_f32 v165, v171, v173
	v_add_f32_e32 v169, v154, v169
	v_exp_f32_e32 v171, v149
	v_add_f32_e32 v169, v155, v169
	v_exp_f32_e32 v172, v150
	v_exp_f32_e32 v173, v151
	v_add_f32_e32 v148, v170, v169
	v_exp_f32_e32 v169, v128
	v_cvt_pk_bf16_f32 v158, v174, v183
	v_exp_f32_e32 v174, v129
	v_cvt_pk_bf16_f32 v166, v175, v176
	v_exp_f32_e32 v175, v130
	v_add_f32_e32 v156, v183, v156
	v_exp_f32_e32 v176, v131
	v_add_f32_e32 v156, v184, v156
	v_cvt_pk_bf16_f32 v167, v177, v178
	v_cvt_pk_bf16_f32 v157, v181, v182
	v_exp_f32_e32 v177, v124
	v_exp_f32_e32 v181, v160
	v_exp_f32_e32 v185, v136
	v_add_f32_e32 v156, v159, v156
	v_add_f32_e32 v148, v171, v148
	v_exp_f32_e32 v178, v125
	v_exp_f32_e32 v182, v161
	v_exp_f32_e32 v186, v137
	v_add_f32_e32 v193, v156, v193
	v_cvt_pk_bf16_f32 v156, v179, v180
	v_add_f32_e32 v148, v172, v148
	v_exp_f32_e32 v179, v126
	v_exp_f32_e32 v183, v162
	v_exp_f32_e32 v187, v138
	v_cvt_pk_bf16_f32 v159, v184, v159
	v_add_f32_e32 v148, v173, v148
	v_exp_f32_e32 v180, v127
	v_exp_f32_e32 v184, v163
	v_exp_f32_e32 v231, v139
	v_add_f32_e32 v218, v148, v218
	v_cvt_pk_bf16_f32 v144, v144, v145
	v_cvt_pk_bf16_f32 v145, v146, v147
	v_cvt_pk_bf16_f32 v146, v140, v141
	v_cvt_pk_bf16_f32 v147, v142, v143
	v_cvt_pk_bf16_f32 v140, v152, v153
	v_cvt_pk_bf16_f32 v141, v154, v155
	ds_read_b64_tr_b16 v[130:131], v224 offset:11520
	ds_read_b64_tr_b16 v[128:129], v224 offset:9216
	ds_read_b64_tr_b16 v[148:149], v224 offset:9248
	ds_read_b64_tr_b16 v[152:153], v224 offset:9280
	ds_read_b64_tr_b16 v[160:161], v224 offset:9312
	ds_read_b64_tr_b16 v[150:151], v224 offset:11552
	ds_read_b64_tr_b16 v[154:155], v224 offset:11584
	ds_read_b64_tr_b16 v[162:163], v224 offset:11616
	v_cvt_pk_bf16_f32 v142, v170, v171
	v_exp_f32_e32 v170, v112
	v_exp_f32_e32 v171, v113
	v_cvt_pk_bf16_f32 v143, v172, v173
	v_exp_f32_e32 v172, v114
	v_cvt_pk_bf16_f32 v124, v169, v174
	v_cvt_pk_bf16_f32 v125, v175, v176
	v_cvt_pk_bf16_f32 v126, v177, v178
	v_cvt_pk_bf16_f32 v127, v179, v180
	v_cvt_pk_bf16_f32 v136, v181, v182
	v_cvt_pk_bf16_f32 v137, v183, v184
	v_cvt_pk_bf16_f32 v138, v185, v186
	v_cvt_pk_bf16_f32 v139, v187, v231
	v_exp_f32_e32 v173, v115
	s_waitcnt lgkmcnt(1)
; __device__ __forceinline__ unsigned cvtpk(float lo, float hi) { f32x2_t v = {lo, hi}; bf16x2_t b = __builtin_convertvector(v, bf16x2_t); return __builtin_bit_cast(unsigned, b); }
; template <int DH, int KT, int NQT, bool PF, class Ctx>
; __device__ __forceinline__ void attn_item(unsigned char* smem, const Ctx& c) {
;     ...
;             for (int j = 0; j < 4; ++j) { const float pv = __builtin_amdgcn_exp2f(s[q][k4][j] - mnew); s[q][k4][j] = pv; psum += pv; }
;           lrow[qt] += psum;
; #pragma unroll
;           for (int kk = 0; kk < NKK; ++kk) {
;             u32x4 w;
;             w.x = cvtpk(s[q][2 * kk][0], s[q][2 * kk][1]); w.y = cvtpk(s[q][2 * kk][2], s[q][2 * kk][3]);
;             w.z = cvtpk(s[q][2 * kk + 1][0], s[q][2 * kk + 1][1]); w.w = cvtpk(s[q][2 * kk + 1][2], s[q][2 * kk + 1][3]);
;             pfa[qt][kk] = __builtin_bit_cast(bf16x8, w);
;           }
;         }
;       }
; #pragma unroll
;       for (int kk = 0; kk < NKK; ++kk) {
;         const bf16_t* vb = sV + (32 * kk + 4 * quad + (l15 >> 2)) * LDK + 4 * (l15 & 3);
; #pragma unroll
;         for (int dt = 0; dt < NDT; ++dt) {
;           const s16x4 lo = tr_read(vb + 16 * dt);
;           const s16x4 hi = tr_read(vb + 16 * LDK + 16 * dt);
;           const bf16x8 vf = (bf16x8){lo[0], lo[1], lo[2], lo[3], hi[0], hi[1], hi[2], hi[3]};
; #pragma unroll
;           for (int qt = 0; qt < NQT; ++qt) o[qt][dt] = __builtin_amdgcn_mfma_f32_16x16x32_bf16(vf, pfa[qt][kk], o[qt][dt], 0, 0, 0);
;         }
;       }
	s_setprio 1
	v_mfma_f32_16x16x32_bf16 v[100:103], v[152:155], v[124:127], v[100:103]
	v_add_f32_e32 v169, 0, v169
	v_cvt_pk_bf16_f32 v113, v172, v173
	s_add_u32 s4, s4, 0x60000
	v_mfma_f32_16x16x32_bf16 v[84:87], v[152:155], v[144:147], v[84:87]
	s_addc_u32 s5, s5, 0
	s_add_i32 s7, s7, 1
	s_cmp_lg_u32 s8, s4
	v_mfma_f32_16x16x32_bf16 v[52:55], v[152:155], v[164:167], v[52:55]
	v_mfma_f32_16x16x32_bf16 v[12:15], v[152:155], v[136:139], v[12:15]
	v_exp_f32_e32 v152, v132
	v_exp_f32_e32 v153, v133
	v_exp_f32_e32 v154, v134
	v_mfma_f32_16x16x32_bf16 v[92:95], v[128:131], v[144:147], v[92:95]
	v_mfma_f32_16x16x32_bf16 v[104:107], v[148:151], v[124:127], v[104:107]
	v_mfma_f32_16x16x32_bf16 v[88:91], v[148:151], v[144:147], v[88:91]
	v_mfma_f32_16x16x32_bf16 v[64:67], v[148:151], v[164:167], v[64:67]
	v_mfma_f32_16x16x32_bf16 v[24:27], v[148:151], v[136:139], v[24:27]
	v_exp_f32_e32 v148, v116
	v_exp_f32_e32 v149, v117
	s_waitcnt lgkmcnt(0)
	v_mfma_f32_16x16x32_bf16 v[68:71], v[160:163], v[144:147], v[68:71]
	v_exp_f32_e32 v144, v135
	v_mfma_f32_16x16x32_bf16 v[32:35], v[128:131], v[136:139], v[32:35]
	v_exp_f32_e32 v150, v118
	v_mfma_f32_16x16x32_bf16 v[0:3], v[160:163], v[136:139], v[0:3]
	v_exp_f32_e32 v136, v121
	v_exp_f32_e32 v137, v122
	v_exp_f32_e32 v151, v119
	v_exp_f32_e32 v145, v120
	ds_read_b64_tr_b16 v[116:117], v224 offset:13824
	ds_read_b64_tr_b16 v[118:119], v224 offset:16128
	v_exp_f32_e32 v138, v123
	v_mfma_f32_16x16x32_bf16 v[108:111], v[128:131], v[124:127], v[108:111]
	v_cvt_pk_bf16_f32 v112, v170, v171
	v_cvt_pk_bf16_f32 v114, v148, v149
	v_cvt_pk_bf16_f32 v115, v150, v151
	v_mfma_f32_16x16x32_bf16 v[76:79], v[128:131], v[164:167], v[76:79]
	v_cvt_pk_bf16_f32 v120, v152, v153
	v_cvt_pk_bf16_f32 v121, v154, v144
	v_cvt_pk_bf16_f32 v122, v145, v136
	v_cvt_pk_bf16_f32 v123, v137, v138
	s_waitcnt lgkmcnt(0)
	v_mfma_f32_16x16x32_bf16 v[108:111], v[116:119], v[112:115], v[108:111]
	v_mfma_f32_16x16x32_bf16 v[92:95], v[116:119], v[140:143], v[92:95]
	v_mfma_f32_16x16x32_bf16 v[76:79], v[116:119], v[156:159], v[76:79]
	v_mfma_f32_16x16x32_bf16 v[32:35], v[116:119], v[120:123], v[32:35]
	v_add_f32_e32 v116, v174, v169
	v_add_f32_e32 v116, v175, v116
	v_add_f32_e32 v116, v176, v116
	v_add_f32_e32 v116, v177, v116
	v_add_f32_e32 v116, v178, v116
	v_add_f32_e32 v116, v179, v116
	v_add_f32_e32 v116, v180, v116
	v_add_f32_e32 v116, v170, v116
	v_add_f32_e32 v116, v171, v116
	v_add_f32_e32 v116, v172, v116
	v_add_f32_e32 v116, v173, v116
	v_add_f32_e32 v116, v148, v116
	v_add_f32_e32 v116, v149, v116
	v_add_f32_e32 v116, v150, v116
	v_add_f32_e32 v116, v151, v116
	v_add_f32_e32 v225, v116, v225
	v_add_f32_e32 v116, 0, v181
	v_add_f32_e32 v116, v182, v116
	v_add_f32_e32 v116, v183, v116
	v_add_f32_e32 v116, v184, v116
	v_add_f32_e32 v116, v185, v116
	v_add_f32_e32 v116, v186, v116
	v_mfma_f32_16x16x32_bf16 v[96:99], v[160:163], v[124:127], v[96:99]
	ds_read_b64_tr_b16 v[124:125], v224 offset:13856
	ds_read_b64_tr_b16 v[128:129], v224 offset:13888
	ds_read_b64_tr_b16 v[132:133], v224 offset:13920
	ds_read_b64_tr_b16 v[126:127], v224 offset:16160
	ds_read_b64_tr_b16 v[130:131], v224 offset:16192
	ds_read_b64_tr_b16 v[134:135], v224 offset:16224
	v_add_f32_e32 v116, v187, v116
	v_add_f32_e32 v116, v231, v116
	v_add_f32_e32 v116, v152, v116
	v_mfma_f32_16x16x32_bf16 v[48:51], v[160:163], v[164:167], v[48:51]
	v_add_f32_e32 v116, v153, v116
	v_add_f32_e32 v116, v154, v116
	s_waitcnt lgkmcnt(2)
	v_mfma_f32_16x16x32_bf16 v[104:107], v[124:127], v[112:115], v[104:107]
	s_waitcnt lgkmcnt(1)
	v_mfma_f32_16x16x32_bf16 v[100:103], v[128:131], v[112:115], v[100:103]
	s_waitcnt lgkmcnt(0)
	v_mfma_f32_16x16x32_bf16 v[96:99], v[132:135], v[112:115], v[96:99]
	v_add_f32_e32 v112, v144, v116
	v_add_f32_e32 v112, v145, v112
	v_add_f32_e32 v112, v136, v112
	v_mfma_f32_16x16x32_bf16 v[88:91], v[124:127], v[140:143], v[88:91]
	v_add_f32_e32 v112, v137, v112
	v_add_f32_e32 v112, v138, v112
	v_add_f32_e32 v191, v112, v191
	v_mfma_f32_16x16x32_bf16 v[64:67], v[124:127], v[156:159], v[64:67]
	v_mfma_f32_16x16x32_bf16 v[24:27], v[124:127], v[120:123], v[24:27]
	v_mfma_f32_16x16x32_bf16 v[84:87], v[128:131], v[140:143], v[84:87]
	v_mfma_f32_16x16x32_bf16 v[52:55], v[128:131], v[156:159], v[52:55]
	v_mfma_f32_16x16x32_bf16 v[12:15], v[128:131], v[120:123], v[12:15]
	v_mfma_f32_16x16x32_bf16 v[68:71], v[132:135], v[140:143], v[68:71]
	v_mfma_f32_16x16x32_bf16 v[48:51], v[132:135], v[156:159], v[48:51]
	v_mfma_f32_16x16x32_bf16 v[0:3], v[132:135], v[120:123], v[0:3]
	s_setprio 0
	s_cbranch_scc0 .LBB0_174

; template <int DH, int KT, int NQT, bool PF, class Ctx>
; __device__ __forceinline__ void attn_item(unsigned char* smem, const Ctx& c) {
;     ...
;       for (int g = 0; g < NQT; g += QG) {
;         f32x4 s[QG][NK4];
; #pragma unroll
;         for (int q = 0; q < QG; ++q)
; #pragma unroll
;           for (int k4 = 0; k4 < NK4; ++k4) s[q][k4] = (f32x4){0.f, 0.f, 0.f, 0.f};
; #pragma unroll
;         for (int k4 = 0; k4 < NK4; ++k4)
; #pragma unroll
;           for (int ks = 0; ks < NKS; ++ks) {
;             const bf16x8 kf = *(const bf16x8*)(sK + (16 * k4 + l15) * LDK + ks * 32 + quad * 8);
; #pragma unroll
;             for (int q = 0; q < QG; ++q) s[q][k4] = __builtin_amdgcn_mfma_f32_16x16x32_bf16(kf, qf[g + q][ks], s[q][k4], 0, 0, 0);
;           }
; #pragma unroll
;         for (int q = 0; q < QG; ++q) {
;           const int qt = g + q;
;           float mx = -1e30f;
; #pragma unroll
;           for (int k4 = 0; k4 < NK4; ++k4)
; #pragma unroll
;             for (int j = 0; j < 4; ++j) { const float v = c.score(t, wid, qt * 16 + l15, 16 * k4 + 4 * quad + j, s[q][k4][j]); s[q][k4][j] = v; mx = fmaxf(mx, v); }
;           mx = fmaxf(mx, __shfl_xor(mx, 16)); mx = fmaxf(mx, __shfl_xor(mx, 32));
;           const float mnew = fmaxf(mrow[qt], mx);
;           if (__any(mnew > mrow[qt])) {
;             const float alpha = __builtin_amdgcn_exp2f(mrow[qt] - mnew);
;             mrow[qt] = mnew;
;             lrow[qt] *= alpha;
; #pragma unroll
;             for (int dt = 0; dt < NDT; ++dt) o[qt][dt] *= alpha;
;           }
.LBB0_215:
	s_setprio 1
	ds_read_b128 v[136:139], v188
	ds_read_b128 v[156:159], v188 offset:64
	ds_read_b128 v[164:167], v188 offset:2304
	ds_read_b128 v[172:175], v188 offset:2368
	ds_read_b128 v[180:183], v188 offset:4608
	ds_read_b128 v[132:135], v188 offset:4672
	ds_read_b128 v[120:123], v188 offset:6912
	s_waitcnt lgkmcnt(6)
	v_mfma_f32_16x16x32_bf16 v[112:115], v[136:139], v[4:7], v[232:235]
	ds_read_b128 v[168:171], v188 offset:6976
	v_cmp_lt_i32_e32 vcc, v215, v216
	s_nop 0
	v_mfma_f32_16x16x32_bf16 v[116:119], v[136:139], v[16:19], v[236:239]
	s_waitcnt lgkmcnt(6)
	v_mfma_f32_16x16x32_bf16 v[128:131], v[156:159], v[8:11], v[112:115]
	s_nop 0
	v_mfma_f32_16x16x32_bf16 v[144:147], v[156:159], v[20:23], v[116:119]
	s_waitcnt lgkmcnt(5)
	v_mfma_f32_16x16x32_bf16 v[112:115], v[164:167], v[4:7], v[232:235]
	v_mfma_f32_16x16x32_bf16 v[116:119], v[164:167], v[16:19], v[236:239]
	s_waitcnt lgkmcnt(4)
	v_mfma_f32_16x16x32_bf16 v[124:127], v[172:175], v[8:11], v[112:115]
	v_mfma_f32_16x16x32_bf16 v[140:143], v[172:175], v[20:23], v[116:119]
	s_waitcnt lgkmcnt(3)
	v_mfma_f32_16x16x32_bf16 v[112:115], v[180:183], v[4:7], v[232:235]
	s_nop 2
	v_cndmask_b32_e32 v116, v214, v215, vcc
	v_lshlrev_b32_e32 v220, 2, v116
	v_max3_f32 v116, v128, s90, v129
	v_max3_f32 v148, v116, v130, v131
	s_waitcnt lgkmcnt(1)
	v_mfma_f32_16x16x32_bf16 v[116:119], v[120:123], v[4:7], v[232:235]
	v_max3_f32 v148, v148, v124, v125
	v_max3_f32 v148, v148, v126, v127
	v_cmp_lt_i32_e32 vcc, v217, v216
	v_mfma_f32_16x16x32_bf16 v[112:115], v[132:135], v[8:11], v[112:115]
	s_nop 0
	v_cndmask_b32_e32 v162, v214, v217, vcc
	v_lshlrev_b32_e32 v223, 2, v162
	s_waitcnt lgkmcnt(0)
	v_mfma_f32_16x16x32_bf16 v[116:119], v[168:171], v[8:11], v[116:119]
	s_nop 2
	v_max3_f32 v148, v148, v112, v113
	v_max3_f32 v148, v148, v114, v115
	s_nop 2
	v_max3_f32 v148, v148, v116, v117
	v_max3_f32 v160, v148, v118, v119
	ds_bpermute_b32 v161, v220, v160
	v_mfma_f32_16x16x32_bf16 v[148:151], v[180:183], v[16:19], v[236:239]
	v_mfma_f32_16x16x32_bf16 v[152:155], v[132:135], v[20:23], v[148:151]
	s_waitcnt lgkmcnt(0)
	s_nop 5
	v_max_f32_e32 v148, v161, v161
	v_max_f32_e32 v160, v160, v148
	v_mfma_f32_16x16x32_bf16 v[148:151], v[120:123], v[16:19], v[236:239]
	ds_bpermute_b32 v161, v223, v160
	s_waitcnt lgkmcnt(0)
	v_max3_f32 v230, v249, v160, v161
	v_mfma_f32_16x16x32_bf16 v[148:151], v[168:171], v[20:23], v[148:151]
	v_cmp_gt_f32_e32 vcc, v230, v249
	s_cbranch_vccz .LBB0_217
	v_max_f32_e32 v160, 0, v230
	v_sub_f32_e32 v232, v232, v230
	v_exp_f32_e64 v160, -v160
	v_sub_f32_e32 v233, v233, v230
	v_sub_f32_e32 v234, v234, v230
	v_sub_f32_e32 v235, v235, v230
	v_mul_f32_e32 v225, v225, v160
	v_pk_mul_f32 v[110:111], v[110:111], v[160:161] op_sel_hi:[1,0]
	v_pk_mul_f32 v[108:109], v[108:109], v[160:161] op_sel_hi:[1,0]
	v_pk_mul_f32 v[106:107], v[106:107], v[160:161] op_sel_hi:[1,0]
	v_pk_mul_f32 v[104:105], v[104:105], v[160:161] op_sel_hi:[1,0]
	v_pk_mul_f32 v[102:103], v[102:103], v[160:161] op_sel_hi:[1,0]
	v_pk_mul_f32 v[100:101], v[100:101], v[160:161] op_sel_hi:[1,0]
	v_pk_mul_f32 v[98:99], v[98:99], v[160:161] op_sel_hi:[1,0]
	v_pk_mul_f32 v[96:97], v[96:97], v[160:161] op_sel_hi:[1,0]
	v_sub_f32_e32 v128, v128, v230
	v_sub_f32_e32 v129, v129, v230
	v_sub_f32_e32 v130, v130, v230
	v_sub_f32_e32 v131, v131, v230
	v_sub_f32_e32 v124, v124, v230
	v_sub_f32_e32 v125, v125, v230
	v_sub_f32_e32 v126, v126, v230
	v_sub_f32_e32 v127, v127, v230
	v_sub_f32_e32 v112, v112, v230
	v_sub_f32_e32 v113, v113, v230
	v_sub_f32_e32 v114, v114, v230
	v_sub_f32_e32 v115, v115, v230
	v_sub_f32_e32 v116, v116, v230
	v_sub_f32_e32 v117, v117, v230
	v_sub_f32_e32 v118, v118, v230
	v_sub_f32_e32 v119, v119, v230
